# A+xcdmap plus hg_seq: XCD-affine task map and prefetch landing registers with counted waits (no back-edge vmcnt(0))
# speedup vs baseline: 1.0080x; 1.0003x over previous
; #define LAS __attribute__((address_space(3)))
; __device__ __forceinline__ int opaque_tid() { int t = threadIdx.x; asm volatile("" : "+v"(t)); return t; }
; __device__ __forceinline__ void hg_seq(const Params& p, LAS unsigned char* lds, int task) {
;     const int tid = opaque_tid(), lane = tid & 63, w = __builtin_amdgcn_readfirstlane(tid >> 6), fr = lane & 15, fq = lane >> 4;
;     unsigned char* ws = p.ws; const bf16_t* phg = (const bf16_t*)(ws + WS_PHG); const bf16_t* oi = (const bf16_t*)(ws + WS_OI); const float* decb = (const float*)(ws + WS_DECB); bf16_t* ob = (bf16_t*)(ws + WS_B);
;     constexpr int QG = 0, KDT = 17408, VT = 35840, ST = 40448;
;     int rowbase, TC, h, vq, nch, dbase; const float* S0 = nullptr; float* Sout;
;     if (task < 128) { const int b = task >> 4; h = (task >> 2) & 3; vq = task & 3; rowbase = b * 4096; TC = 64; nch = 64; dbase = (b * 4 + h) * 64; Sout = p.out + O_PHG + (size_t)(b * 4 + h) * 16384; }
;     else { const int s = task - 128, b = s >> 4; h = (s >> 2) & 3; vq = s & 3; rowbase = NTOKP + b * 32; TC = 32; nch = 1; dbase = 2048 + b * 4 + h; S0 = p.in[5] + (size_t)(b * 4 + h) * 16384; Sout = p.out + O_SHG + (size_t)(b * 4 + h) * 16384; }
; __device__ __forceinline__ void ph_hgseq(const Params& p, LAS unsigned char* lds, int first, int nblk) {
; #pragma unroll 1
;     for (int t = (int)blockIdx.x - first; t < 384; t += nblk) hg_seq(p, lds, t);
; }
.LBB0_572:
	s_and_b64 vcc, exec, s[0:1]
	s_cbranch_vccz .LBB0_681
	s_cmpk_lt_i32 s2, 0x80
	s_cbranch_scc1 .LBB0_647
	s_add_i32 s35, s2, 0xffffff80
	s_cmpk_gt_u32 s35, 0x17f
	s_cbranch_scc1 .LBB0_648
	s_and_b32 s0, s35, 7
	s_lshr_b32 s1, s35, 3
	s_lshl_b32 s0, s0, 2
	s_lshr_b32 s35, s1, 2
	s_add_i32 s0, s0, s35
	s_lshl_b32 s0, s0, 2
	s_and_b32 s1, s1, 3
	s_or_b32 s35, s0, s1
	s_add_u32 s60, s92, 0x1b9b6800
	s_addc_u32 s61, s93, 0
	s_add_u32 s15, s92, 0x1da36800
	s_addc_u32 s18, s93, 0
	s_add_u32 s19, s90, 0x950e000
	s_addc_u32 s33, s91, 0
	s_add_u32 s50, s90, 0x8200000
	s_addc_u32 s51, s91, 0
	s_bfe_u32 s84, s35, 0x20002
	s_and_b32 s85, s35, 3
	s_lshl_b32 s96, s85, 5
	s_lshl_b32 s0, s84, 8
	s_add_u32 s0, s92, s0
	s_addc_u32 s1, s93, 0
	s_add_u32 s64, s0, 0x22c0000
	s_mov_b32 s53, 0
	s_addc_u32 s65, s1, 0
	s_and_b32 s0, s35, 15
	s_waitcnt lgkmcnt(0)
	s_mul_i32 s68, s0, 0x8200
	s_mov_b32 s69, s53
	v_mov_b32_e32 v0, 0
	s_movk_i32 s97, 0x110
	s_movk_i32 s3, 0x90
	s_mov_b32 s14, s35
	s_branch .LBB0_577

; __device__ __forceinline__ void hg_seq(const Params& p, LAS unsigned char* lds, int task) {
;     ...
;     auto gload = [&](HgR& R, int ch) {
;         const int row0 = rowbase + ch * 64;
; #pragma unroll
;         for (int j = 0; j < 2; ++j) {
;             const int r = prow + j * 32; const bool ok = r < TC;
;             const bf16_t* src = phg + (size_t)(row0 + (ok ? r : 0)) * HGC + h * 128 + pcol * 8;
;             R.gq[j] = *(const u32x4*)src; R.gk[j] = *(const u32x4*)(src + 512);
;         }
;         if (tid < 256) {
;             const int r = tid >> 4; const bool ok = r < (TC >> 2);
;             const bf16_t* src = phg + (size_t)(row0 + ((vq * 32 * TC) >> 7) + (ok ? r : 0)) * HGC + 1024 + h * 128 + pcol * 8;
;             R.gv = *(const u32x4*)src;
;         }
;         { const int t = tt * 16 + fr; const bool ok = t < TC; R.go = *(const u32x2*)(oi + ((size_t)(h * 4 + vq) * NTOK + row0 + (ok ? t : 0)) * 32 + vt_o * 16 + fq * 4); }
;         R.gdec = *(const f32x4*)(decb + (size_t)(dbase + ch) * 128 + w * 16 + fq * 4);
;     };
;     HgR ra, rb;
;     gload(ra, 0); if (nch > 1) gload(rb, 1);
.LBB0_599:
	s_or_b64 exec, exec, s[10:11]
	s_ashr_i32 s10, s13, 3
	v_and_or_b32 v2, s10, -16, v66
	v_cmp_gt_i32_e64 s[10:11], s58, v2
	s_mov_b32 s73, s53
	s_and_b32 s62, s12, 16
	v_cndmask_b32_e64 v34, 0, v2, s[10:11]
	v_ashrrev_i32_e32 v35, 31, v34
	v_lshl_add_u64 v[74:75], s[68:69], 0, v[34:35]
	s_mov_b32 s77, s53
	v_lshl_add_u64 v[34:35], v[74:75], 0, s[72:73]
	s_lshl_b32 s52, s62, 1
	s_lshl_b64 s[16:17], s[76:77], 9
	v_lshlrev_b64 v[34:35], 6, v[34:35]
	s_add_u32 s63, s15, s16
	v_lshl_add_u64 v[34:35], s[60:61], 0, v[34:35]
	s_addc_u32 s67, s18, s17
	s_ashr_i32 s13, s12, 31
	v_lshl_add_u64 v[34:35], v[34:35], 0, s[52:53]
	v_lshlrev_b32_e32 v58, 1, v32
	v_mov_b32_e32 v59, v0
	s_lshl_b64 s[16:17], s[12:13], 2
	v_lshl_add_u64 v[34:35], v[34:35], 0, v[58:59]
	s_add_u32 s66, s63, s16
	s_addc_u32 s67, s67, s17
	v_lshlrev_b32_e32 v64, 2, v32
	global_load_dwordx2 v[116:117], v[34:35], off
	global_load_dwordx4 v[120:123], v64, s[66:67]
	s_and_b64 vcc, exec, s[54:55]
	s_cbranch_vccz .LBB0_603
	s_add_i32 s78, s72, 64
	v_add_u32_e32 v32, s78, v68
	v_add_u32_e32 v40, s78, v71
	v_ashrrev_i32_e32 v33, 31, v32
	v_ashrrev_i32_e32 v41, 31, v40
	v_lshlrev_b64 v[32:33], 12, v[32:33]
	v_lshlrev_b64 v[40:41], 12, v[40:41]
	v_lshl_add_u64 v[32:33], s[64:65], 0, v[32:33]
	v_mov_b32_e32 v57, v0
	v_lshl_add_u64 v[40:41], s[64:65], 0, v[40:41]
	v_lshl_add_u64 v[32:33], v[32:33], 0, v[56:57]
	v_lshl_add_u64 v[40:41], v[40:41], 0, v[56:57]
	global_load_dwordx4 v[36:39], v[32:33], off
	s_nop 0
	global_load_dwordx4 v[32:35], v[32:33], off offset:1024
	s_nop 0
	global_load_dwordx4 v[44:47], v[40:41], off
	s_nop 0
	global_load_dwordx4 v[40:43], v[40:41], off offset:1024
	s_and_saveexec_b64 s[80:81], s[8:9]
	s_cbranch_execz .LBB0_602
	s_lshr_b32 s13, s58, 2
	s_mul_i32 s63, s58, s96
	s_lshr_b32 s63, s63, 7
	v_cmp_gt_i32_e32 vcc, s13, v3
	s_add_i32 s13, s78, s63
	s_nop 0
	v_cndmask_b32_e32 v48, 0, v3, vcc
	v_add_u32_e32 v48, s13, v48
	v_ashrrev_i32_e32 v49, 31, v48
	v_lshlrev_b64 v[48:49], 12, v[48:49]
	v_lshl_add_u64 v[48:49], s[64:65], 0, v[48:49]
	v_lshl_add_u64 v[48:49], v[48:49], 0, v[56:57]
	global_load_dwordx4 v[48:51], v[48:49], off offset:2048
.LBB0_602:
	s_or_b64 exec, exec, s[80:81]
	s_mov_b32 s79, s53
	v_lshl_add_u64 v[52:53], v[74:75], 0, s[78:79]
	s_add_i32 s66, s76, 1
	s_mov_b32 s67, s53
	v_lshlrev_b64 v[52:53], 6, v[52:53]
	s_lshl_b64 s[66:67], s[66:67], 9
	v_lshl_add_u64 v[52:53], s[60:61], 0, v[52:53]
	s_add_u32 s13, s15, s66
	v_lshl_add_u64 v[52:53], v[52:53], 0, s[52:53]
	v_mov_b32_e32 v59, v0
	s_addc_u32 s63, s18, s67
	v_lshl_add_u64 v[52:53], v[52:53], 0, v[58:59]
	s_add_u32 s66, s13, s16
	s_addc_u32 s67, s63, s17
	global_load_dwordx2 v[118:119], v[52:53], off
	s_nop 0
	global_load_dwordx4 v[124:127], v64, s[66:67]
	s_mov_b32 s63, 6
	s_movk_i32 s66, 0x70
	s_branch .LBB0_604
.LBB0_603:
	s_waitcnt vmcnt(0)
	s_mov_b32 s63, 5
	s_mov_b32 s66, 48

; #define LAS __attribute__((address_space(3)))
; __device__ __forceinline__ void hg_seq(const Params& p, LAS unsigned char* lds, int task) {
;     ...
;     auto body = [&](HgR& R, int ch) {
;         const int row0 = rowbase + ch * 64;
; #pragma unroll
;         for (int j = 0; j < 2; ++j) {
;             const int r = prow + j * 32; const u32x4 z4 = (u32x4){0u, 0u, 0u, 0u};
;             *(LAS u32x4*)(lds + QG + r * 272 + pcol * 16) = (r < TC) ? R.gq[j] : z4;
;             if (TC == 64) { const int lin = r * 128 + pcol * 8; *(LAS u32x4*)(lds + KDT + (lin >> 6) * 144 + (lin & 63) * 2) = R.gk[j]; }
;             else if (r < 32) { const int lin = r * 128 + pcol * 8; *(LAS u32x4*)(lds + KDT + (lin >> 5) * 144 + (lin & 31) * 2) = R.gk[j]; }
;         }
.LBB0_605:
	s_waitcnt vmcnt(11)
	v_cndmask_b32_e64 v59, 0, v11, s[4:5]
	v_cndmask_b32_e64 v58, 0, v10, s[4:5]
	v_cndmask_b32_e64 v57, 0, v9, s[4:5]
	v_cndmask_b32_e64 v56, 0, v8, s[4:5]
	ds_write_b128 v101, v[56:59]
	s_and_saveexec_b64 s[54:55], s[16:17]
	s_cbranch_execz .LBB0_607
	v_add_u32_e32 v1, v98, v99
	s_waitcnt vmcnt(10)
	ds_write_b128 v1, v[12:15] offset:17408
.LBB0_607:
	s_or_b64 exec, exec, s[54:55]
	s_waitcnt vmcnt(9)
	v_cndmask_b32_e64 v59, 0, v19, s[6:7]
	v_cndmask_b32_e64 v58, 0, v18, s[6:7]
	v_cndmask_b32_e64 v57, 0, v17, s[6:7]
	v_cndmask_b32_e64 v56, 0, v16, s[6:7]
	ds_write_b128 v101, v[56:59] offset:8704
	s_and_saveexec_b64 s[54:55], s[0:1]
	s_cbranch_execnz .LBB0_610
	s_or_b64 exec, exec, s[54:55]
	s_and_saveexec_b64 s[80:81], s[78:79]
	s_cbranch_execnz .LBB0_611

; #define LAS __attribute__((address_space(3)))
; __device__ __forceinline__ void hg_seq(const Params& p, LAS unsigned char* lds, int task) {
;     ...
;             if (TC == 64) { const int lin = r * 128 + pcol * 8; *(LAS u32x4*)(lds + KDT + (lin >> 6) * 144 + (lin & 63) * 2) = R.gk[j]; }
;             else if (r < 32) { const int lin = r * 128 + pcol * 8; *(LAS u32x4*)(lds + KDT + (lin >> 5) * 144 + (lin & 31) * 2) = R.gk[j]; }
;         }
.LBB0_610:
	v_add_u32_e32 v1, v100, v99
	s_waitcnt vmcnt(8)
	ds_write_b128 v1, v[20:23] offset:17408
	s_or_b64 exec, exec, s[54:55]
	s_and_saveexec_b64 s[80:81], s[78:79]
	s_cbranch_execz .LBB0_609

; #define LAS __attribute__((address_space(3)))
; __device__ __forceinline__ void hg_seq(const Params& p, LAS unsigned char* lds, int task) {
;     ...
;         if (TC == 32 && tid < 256) {
; #pragma unroll
;             for (int j = 0; j < 2; ++j) { const int i2 = tid + j * 256; *(LAS u32x4*)(lds + KDT + (i2 >> 2) * 144 + 64 + (i2 & 3) * 16) = (u32x4){0u, 0u, 0u, 0u}; }
;         }
;         if (tid < 256) {
;             const int r = tid >> 4; const int lin = r * 128 + pcol * 8;
;             if (TC == 64) *(LAS u32x4*)(lds + VT + (lin >> 6) * 144 + (lin & 63) * 2) = R.gv;
;             else { if (r < 8) *(LAS u32x4*)(lds + VT + (lin >> 5) * 144 + (lin & 31) * 2) = R.gv;
;                    *(LAS u32x4*)(lds + VT + (tid >> 3) * 144 + 64 + (tid & 3) * 16 + ((tid >> 2) & 1) * 0) = (u32x4){0u, 0u, 0u, 0u}; }
;         }
.LBB0_612:
	s_waitcnt vmcnt(9)
	v_mov_b64_e32 v[58:59], v[26:27]
	s_movk_i32 s52, 0x70
	s_andn2_b64 vcc, exec, s[70:71]
	v_mov_b32_e32 v64, v72
	v_mov_b32_e32 v65, v96
	v_mov_b64_e32 v[56:57], v[24:25]
	s_cbranch_vccnz .LBB0_616
	s_and_saveexec_b64 s[80:81], s[12:13]
	v_add_u32_e32 v1, v93, v94
	ds_write_b128 v1, v[24:27] offset:35840
	s_or_b64 exec, exec, s[80:81]
	v_mov_b32_e32 v2, v0
	v_mov_b32_e32 v3, v0
	v_mov_b32_e32 v1, v0
	v_mov_b64_e32 v[58:59], v[2:3]
	s_mov_b32 s52, 48
	v_mov_b32_e32 v64, v90
	v_mov_b32_e32 v65, v95
	v_mov_b64_e32 v[56:57], v[0:1]

; #define LAS __attribute__((address_space(3)))
; __device__ __forceinline__ unsigned cvt_pk_bf16(float lo, float hi) { f32x2 f = {lo, hi}; bf16x2_t v = __builtin_convertvector(f, bf16x2_t); return __builtin_bit_cast(unsigned, v); }
; __device__ __forceinline__ float bf_lo(unsigned w) { return __uint_as_float(w << 16); }
; __device__ __forceinline__ float bf_hi(unsigned w) { return __uint_as_float(w & 0xffff0000u); }
; __device__ __forceinline__ void hg_seq(const Params& p, LAS unsigned char* lds, int task) {
;     ...
;     auto gload = [&](HgR& R, int ch) {
;         const int row0 = rowbase + ch * 64;
; #pragma unroll
;         for (int j = 0; j < 2; ++j) {
;             const int r = prow + j * 32; const bool ok = r < TC;
;             const bf16_t* src = phg + (size_t)(row0 + (ok ? r : 0)) * HGC + h * 128 + pcol * 8;
;             R.gq[j] = *(const u32x4*)src; R.gk[j] = *(const u32x4*)(src + 512);
;         }
;         if (tid < 256) {
;             const int r = tid >> 4; const bool ok = r < (TC >> 2);
;             const bf16_t* src = phg + (size_t)(row0 + ((vq * 32 * TC) >> 7) + (ok ? r : 0)) * HGC + 1024 + h * 128 + pcol * 8;
;             R.gv = *(const u32x4*)src;
;         }
;         { const int t = tt * 16 + fr; const bool ok = t < TC; R.go = *(const u32x2*)(oi + ((size_t)(h * 4 + vq) * NTOK + row0 + (ok ? t : 0)) * 32 + vt_o * 16 + fq * 4); }
;         R.gdec = *(const f32x4*)(decb + (size_t)(dbase + ch) * 128 + w * 16 + fq * 4);
;     ...
; #pragma unroll
;         for (int vt = 0; vt < 2; ++vt) { u32x2 wv; wv.x = cvt_pk_bf16(S[vt][0], S[vt][1]); wv.y = cvt_pk_bf16(S[vt][2], S[vt][3]); *(LAS u32x2*)(lds + ST + (vt * 16 + fr) * 272 + (w * 16 + fq * 4) * 2) = wv; }
;         const float oi0 = bf_lo(R.go.x), oi1 = bf_hi(R.go.x), oi2 = bf_lo(R.go.y), oi3 = bf_hi(R.go.y);
;         S[0] = S[0] * R.gdec; S[1] = S[1] * R.gdec;
;         __syncthreads();
;         if (ch + 2 < nch) gload(R, ch + 2);
.LBB0_617:
	s_or_b64 exec, exec, s[54:55]
	s_add_i32 s58, s59, 2
	s_cmp_ge_u32 s58, s86
	v_cvt_pk_bf16_f32 v2, v4, v5
	v_cvt_pk_bf16_f32 v3, v6, v7
	s_cselect_b64 s[80:81], -1, 0
	ds_write_b64 v102, v[2:3] offset:40448
	v_cvt_pk_bf16_f32 v2, v28, v29
	v_cvt_pk_bf16_f32 v3, v30, v31
	s_and_b64 vcc, exec, s[80:81]
	ds_write_b64 v102, v[2:3] offset:44800
	s_waitcnt vmcnt(7)
	v_mov_b64_e32 v[88:89], v[116:117]
	s_waitcnt vmcnt(6)
	v_mov_b64_e32 v[60:61], v[120:121]
	v_mov_b64_e32 v[62:63], v[122:123]
	s_waitcnt lgkmcnt(0)
	s_barrier
	s_cbranch_vccnz .LBB0_621
	v_add_u32_e32 v1, s72, v68
	v_add_u32_e32 v2, 0x80, v1
	v_ashrrev_i32_e32 v3, 31, v2
	v_lshlrev_b64 v[2:3], 12, v[2:3]
	v_lshl_add_u64 v[2:3], v[76:77], 0, v[2:3]
	v_add_u32_e32 v1, s72, v71
	global_load_dwordx4 v[8:11], v[2:3], off
	global_load_dwordx4 v[12:15], v[2:3], off offset:1024
	v_add_u32_e32 v2, 0x80, v1
	v_ashrrev_i32_e32 v3, 31, v2
	v_lshlrev_b64 v[2:3], 12, v[2:3]
	v_lshl_add_u64 v[2:3], v[76:77], 0, v[2:3]
	global_load_dwordx4 v[16:19], v[2:3], off
	global_load_dwordx4 v[20:23], v[2:3], off offset:1024
	s_and_saveexec_b64 s[54:55], s[8:9]
	s_cbranch_execz .LBB0_620
	v_add_u32_e32 v1, s72, v97
	v_add_u32_e32 v2, 0x80, v1
	v_ashrrev_i32_e32 v3, 31, v2
	v_lshlrev_b64 v[2:3], 12, v[2:3]
	v_lshl_add_u64 v[2:3], v[76:77], 0, v[2:3]
	global_load_dwordx4 v[24:27], v[2:3], off offset:2048
.LBB0_620:
	s_or_b64 exec, exec, s[54:55]
	s_add_i32 s54, s72, 0x80
	s_ashr_i32 s55, s54, 31
	s_add_i32 s52, s76, s59
	v_lshl_add_u64 v[2:3], v[74:75], 0, s[54:55]
	s_add_i32 s52, s52, 2
	v_lshlrev_b64 v[2:3], 6, v[2:3]
	s_lshl_b64 s[54:55], s[52:53], 9
	v_lshl_add_u64 v[2:3], v[78:79], 0, v[2:3]
	v_lshl_add_u64 v[56:57], v[80:81], 0, s[54:55]
	global_load_dwordx2 v[116:117], v[2:3], off
	s_nop 0
	global_load_dwordx4 v[120:123], v[56:57], off
	s_branch .LBB0_622

; #define LAS __attribute__((address_space(3)))
; __device__ __forceinline__ unsigned cvt_pk_bf16(float lo, float hi) { f32x2 f = {lo, hi}; bf16x2_t v = __builtin_convertvector(f, bf16x2_t); return __builtin_bit_cast(unsigned, v); }
; __device__ __forceinline__ void hg_seq(const Params& p, LAS unsigned char* lds, int task) {
;     ...
;     auto body = [&](HgR& R, int ch) {
;         const int row0 = rowbase + ch * 64;
; #pragma unroll
;         for (int j = 0; j < 2; ++j) {
;             const int r = prow + j * 32; const u32x4 z4 = (u32x4){0u, 0u, 0u, 0u};
;             *(LAS u32x4*)(lds + QG + r * 272 + pcol * 16) = (r < TC) ? R.gq[j] : z4;
;             if (TC == 64) { const int lin = r * 128 + pcol * 8; *(LAS u32x4*)(lds + KDT + (lin >> 6) * 144 + (lin & 63) * 2) = R.gk[j]; }
;             else if (r < 32) { const int lin = r * 128 + pcol * 8; *(LAS u32x4*)(lds + KDT + (lin >> 5) * 144 + (lin & 31) * 2) = R.gk[j]; }
;         }
;     ...
;         {
;             f32x4 a = {0.f, 0.f, 0.f, 0.f};
; #pragma unroll
;             for (int ks = 0; ks < 4; ++ks) {
;                 const bf16x8 sf = *(const LAS bf16x8*)(lds + ST + (vt_o * 16 + fr) * 272 + (ks * 32 + fq * 8) * 2);
;                 const bf16x8 qf = *(const LAS bf16x8*)(lds + QG + (tt * 16 + fr) * 272 + (ks * 32 + fq * 8) * 2);
;                 a = __builtin_amdgcn_mfma_f32_16x16x32_bf16(sf, qf, a, 0, 0, 0);
;             }
;             const int t = tt * 16 + fr;
;             if (t < TC) {
;                 u32x2 wv; wv.x = cvt_pk_bf16(a[0] + oi0, a[1] + oi1); wv.y = cvt_pk_bf16(a[2] + oi2, a[3] + oi3);
;                 *(u32x2*)((bf16_t*)oi + ((size_t)(h * 4 + vq) * NTOK + row0 + t) * 32 + vt_o * 16 + fq * 4) = wv;
;             }
;         }
; #pragma unroll
;         for (int vt = 0; vt < 2; ++vt) {
; #pragma unroll
;             for (int ks = 0; ks < 2; ++ks) {
;                 const bf16x8 kf = *(const LAS bf16x8*)(lds + KDT + (w * 16 + fr) * 144 + (ks * 32 + fq * 8) * 2);
;                 const bf16x8 vf = *(const LAS bf16x8*)(lds + VT + (vt * 16 + fr) * 144 + (ks * 32 + fq * 8) * 2);
;                 S[vt] = __builtin_amdgcn_mfma_f32_16x16x32_bf16(kf, vf, S[vt], 0, 0, 0);
;             }
;         }
.LBB0_622:
	ds_read_b128 v[64:67], v103 offset:40448
	ds_read_b128 v[108:111], v104
	s_waitcnt lgkmcnt(0)
	v_mfma_f32_16x16x32_bf16 v[64:67], v[64:67], v[108:111], 0
	ds_read_b128 v[108:111], v103 offset:40512
	ds_read_b128 v[112:115], v104 offset:64
	s_waitcnt lgkmcnt(0)
	v_mfma_f32_16x16x32_bf16 v[64:67], v[108:111], v[112:115], v[64:67]
	ds_read_b128 v[108:111], v103 offset:40576
	ds_read_b128 v[112:115], v104 offset:128
	s_waitcnt lgkmcnt(0)
	v_mfma_f32_16x16x32_bf16 v[64:67], v[108:111], v[112:115], v[64:67]
	ds_read_b128 v[108:111], v103 offset:40640
	ds_read_b128 v[112:115], v104 offset:192
	s_waitcnt lgkmcnt(0)
	v_mfma_f32_16x16x32_bf16 v[64:67], v[108:111], v[112:115], v[64:67]
	s_and_saveexec_b64 s[54:55], s[10:11]
	s_cbranch_execz .LBB0_624
	v_lshlrev_b32_e32 v2, 16, v88
	v_and_b32_e32 v3, 0xffff0000, v88
	v_lshlrev_b32_e32 v88, 16, v89
	v_and_b32_e32 v89, 0xffff0000, v89
	s_nop 0
	v_pk_add_f32 v[2:3], v[64:65], v[2:3]
	v_pk_add_f32 v[64:65], v[66:67], v[88:89]
	s_ashr_i32 s73, s72, 31
	v_cvt_pk_bf16_f32 v2, v2, v3
	v_cvt_pk_bf16_f32 v3, v64, v65
	v_lshl_add_u64 v[64:65], v[82:83], 0, s[72:73]
	v_lshlrev_b64 v[64:65], 6, v[64:65]
	v_lshl_add_u64 v[64:65], v[78:79], 0, v[64:65]
	global_store_dwordx2 v[64:65], v[2:3], off
.LBB0_624:
	s_or_b64 exec, exec, s[54:55]
	v_pk_mul_f32 v[6:7], v[6:7], v[62:63]
	v_pk_mul_f32 v[4:5], v[4:5], v[60:61]
	v_pk_mul_f32 v[30:31], v[30:31], v[62:63]
	v_pk_mul_f32 v[28:29], v[28:29], v[60:61]
	ds_read_b128 v[60:63], v105 offset:17408
	ds_read_b128 v[64:67], v106 offset:35840
	s_waitcnt lgkmcnt(0)
	v_mfma_f32_16x16x32_bf16 v[2:5], v[60:63], v[64:67], v[4:7]
	ds_read_b128 v[64:67], v105 offset:17472
	ds_read_b128 v[108:111], v106 offset:35904
	s_add_i32 s52, s59, 1
	s_cmp_ge_u32 s52, s86
	s_waitcnt lgkmcnt(0)
	v_mfma_f32_16x16x32_bf16 v[4:7], v[64:67], v[108:111], v[2:5]
	ds_read_b128 v[108:111], v106 offset:38144
	s_waitcnt lgkmcnt(0)
	v_mfma_f32_16x16x32_bf16 v[28:31], v[60:63], v[108:111], v[28:31]
	ds_read_b128 v[60:63], v106 offset:38208
	s_waitcnt lgkmcnt(0)
	s_barrier
	v_mfma_f32_16x16x32_bf16 v[28:31], v[64:67], v[60:63], v[28:31]
	s_cbranch_scc1 .LBB0_630
	s_waitcnt vmcnt(11)
	v_cndmask_b32_e64 v63, 0, v39, s[4:5]
	v_cndmask_b32_e64 v62, 0, v38, s[4:5]
	v_cndmask_b32_e64 v61, 0, v37, s[4:5]
	v_cndmask_b32_e64 v60, 0, v36, s[4:5]
	ds_write_b128 v101, v[60:63]
	s_and_saveexec_b64 s[54:55], s[16:17]
	v_add_u32_e32 v1, v98, v99
	s_waitcnt vmcnt(10)
	ds_write_b128 v1, v[32:35] offset:17408
	s_or_b64 exec, exec, s[54:55]
	s_waitcnt vmcnt(9)
	v_cndmask_b32_e64 v63, 0, v47, s[6:7]
	v_cndmask_b32_e64 v62, 0, v46, s[6:7]
	v_cndmask_b32_e64 v61, 0, v45, s[6:7]
	v_cndmask_b32_e64 v60, 0, v44, s[6:7]
	ds_write_b128 v101, v[60:63] offset:8704
	s_and_saveexec_b64 s[54:55], s[0:1]
	s_cbranch_execnz .LBB0_631
	s_or_b64 exec, exec, s[54:55]
	s_and_saveexec_b64 s[82:83], s[78:79]
	s_cbranch_execnz .LBB0_632

; #define LAS __attribute__((address_space(3)))
; __device__ __forceinline__ void hg_seq(const Params& p, LAS unsigned char* lds, int task) {
;     ...
;             if (TC == 64) { const int lin = r * 128 + pcol * 8; *(LAS u32x4*)(lds + KDT + (lin >> 6) * 144 + (lin & 63) * 2) = R.gk[j]; }
;             else if (r < 32) { const int lin = r * 128 + pcol * 8; *(LAS u32x4*)(lds + KDT + (lin >> 5) * 144 + (lin & 31) * 2) = R.gk[j]; }
;         }
.LBB0_631:
	v_add_u32_e32 v1, v100, v99
	s_waitcnt vmcnt(8)
	ds_write_b128 v1, v[40:43] offset:17408
	s_or_b64 exec, exec, s[54:55]
	s_and_saveexec_b64 s[82:83], s[78:79]
	s_cbranch_execz .LBB0_629

; #define LAS __attribute__((address_space(3)))
; __device__ __forceinline__ void hg_seq(const Params& p, LAS unsigned char* lds, int task) {
;     ...
;         if (TC == 32 && tid < 256) {
; #pragma unroll
;             for (int j = 0; j < 2; ++j) { const int i2 = tid + j * 256; *(LAS u32x4*)(lds + KDT + (i2 >> 2) * 144 + 64 + (i2 & 3) * 16) = (u32x4){0u, 0u, 0u, 0u}; }
;         }
;         if (tid < 256) {
;             const int r = tid >> 4; const int lin = r * 128 + pcol * 8;
;             if (TC == 64) *(LAS u32x4*)(lds + VT + (lin >> 6) * 144 + (lin & 63) * 2) = R.gv;
;             else { if (r < 8) *(LAS u32x4*)(lds + VT + (lin >> 5) * 144 + (lin & 31) * 2) = R.gv;
;                    *(LAS u32x4*)(lds + VT + (tid >> 3) * 144 + 64 + (tid & 3) * 16 + ((tid >> 2) & 1) * 0) = (u32x4){0u, 0u, 0u, 0u}; }
;         }
.LBB0_633:
	s_waitcnt vmcnt(9)
	v_mov_b64_e32 v[62:63], v[50:51]
	s_movk_i32 s52, 0x70
	s_andn2_b64 vcc, exec, s[70:71]
	v_mov_b32_e32 v64, v72
	v_mov_b32_e32 v65, v96
	v_mov_b64_e32 v[60:61], v[48:49]
	s_cbranch_vccnz .LBB0_637
	s_and_saveexec_b64 s[82:83], s[12:13]
	v_add_u32_e32 v1, v93, v94
	ds_write_b128 v1, v[48:51] offset:35840
	s_or_b64 exec, exec, s[82:83]
	v_mov_b32_e32 v2, v0
	v_mov_b32_e32 v3, v0
	v_mov_b32_e32 v1, v0
	v_mov_b64_e32 v[62:63], v[2:3]
	s_mov_b32 s52, 48
	v_mov_b32_e32 v64, v90
	v_mov_b32_e32 v65, v95
	v_mov_b64_e32 v[60:61], v[0:1]

; #define LAS __attribute__((address_space(3)))
; __device__ __forceinline__ unsigned cvt_pk_bf16(float lo, float hi) { f32x2 f = {lo, hi}; bf16x2_t v = __builtin_convertvector(f, bf16x2_t); return __builtin_bit_cast(unsigned, v); }
; __device__ __forceinline__ float bf_lo(unsigned w) { return __uint_as_float(w << 16); }
; __device__ __forceinline__ float bf_hi(unsigned w) { return __uint_as_float(w & 0xffff0000u); }
; __device__ __forceinline__ void hg_seq(const Params& p, LAS unsigned char* lds, int task) {
;     ...
; #pragma unroll
;         for (int vt = 0; vt < 2; ++vt) { u32x2 wv; wv.x = cvt_pk_bf16(S[vt][0], S[vt][1]); wv.y = cvt_pk_bf16(S[vt][2], S[vt][3]); *(LAS u32x2*)(lds + ST + (vt * 16 + fr) * 272 + (w * 16 + fq * 4) * 2) = wv; }
;         const float oi0 = bf_lo(R.go.x), oi1 = bf_hi(R.go.x), oi2 = bf_lo(R.go.y), oi3 = bf_hi(R.go.y);
;         S[0] = S[0] * R.gdec; S[1] = S[1] * R.gdec;
;         __syncthreads();
;         if (ch + 2 < nch) gload(R, ch + 2);
;         {
;             f32x4 a = {0.f, 0.f, 0.f, 0.f};
; #pragma unroll
;             for (int ks = 0; ks < 4; ++ks) {
;                 const bf16x8 sf = *(const LAS bf16x8*)(lds + ST + (vt_o * 16 + fr) * 272 + (ks * 32 + fq * 8) * 2);
;                 const bf16x8 qf = *(const LAS bf16x8*)(lds + QG + (tt * 16 + fr) * 272 + (ks * 32 + fq * 8) * 2);
;                 a = __builtin_amdgcn_mfma_f32_16x16x32_bf16(sf, qf, a, 0, 0, 0);
;             }
;             const int t = tt * 16 + fr;
;             if (t < TC) {
;                 u32x2 wv; wv.x = cvt_pk_bf16(a[0] + oi0, a[1] + oi1); wv.y = cvt_pk_bf16(a[2] + oi2, a[3] + oi3);
;                 *(u32x2*)((bf16_t*)oi + ((size_t)(h * 4 + vq) * NTOK + row0 + t) * 32 + vt_o * 16 + fq * 4) = wv;
;             }
.LBB0_638:
	s_or_b64 exec, exec, s[54:55]
	v_cvt_pk_bf16_f32 v2, v4, v5
	v_cvt_pk_bf16_f32 v3, v6, v7
	s_add_i32 s52, s59, 3
	ds_write_b64 v102, v[2:3] offset:40448
	v_cvt_pk_bf16_f32 v2, v28, v29
	v_cvt_pk_bf16_f32 v3, v30, v31
	s_cmp_ge_u32 s52, s86
	ds_write_b64 v102, v[2:3] offset:44800
	s_waitcnt vmcnt(7)
	v_mov_b64_e32 v[84:85], v[118:119]
	s_waitcnt vmcnt(6)
	v_mov_b64_e32 v[52:53], v[124:125]
	v_mov_b64_e32 v[54:55], v[126:127]
	s_waitcnt lgkmcnt(0)
	s_barrier
	s_cbranch_scc1 .LBB0_642
	v_add_u32_e32 v1, s72, v68
	v_add_u32_e32 v2, 0xc0, v1
	v_ashrrev_i32_e32 v3, 31, v2
	v_lshlrev_b64 v[2:3], 12, v[2:3]
	v_lshl_add_u64 v[2:3], v[76:77], 0, v[2:3]
	v_add_u32_e32 v1, s72, v71
	global_load_dwordx4 v[36:39], v[2:3], off
	global_load_dwordx4 v[32:35], v[2:3], off offset:1024
	v_add_u32_e32 v2, 0xc0, v1
	v_ashrrev_i32_e32 v3, 31, v2
	v_lshlrev_b64 v[2:3], 12, v[2:3]
	v_lshl_add_u64 v[2:3], v[76:77], 0, v[2:3]
	global_load_dwordx4 v[44:47], v[2:3], off
	global_load_dwordx4 v[40:43], v[2:3], off offset:1024
	s_and_saveexec_b64 s[54:55], s[8:9]
	s_cbranch_execz .LBB0_641
	v_add_u32_e32 v1, s72, v97
	v_add_u32_e32 v2, 0xc0, v1
	v_ashrrev_i32_e32 v3, 31, v2
	v_lshlrev_b64 v[2:3], 12, v[2:3]
	v_lshl_add_u64 v[2:3], v[76:77], 0, v[2:3]
	global_load_dwordx4 v[48:51], v[2:3], off offset:2048
.LBB0_641:
	s_or_b64 exec, exec, s[54:55]
	s_add_i32 s54, s72, 0xc0
	s_ashr_i32 s55, s54, 31
	v_lshl_add_u64 v[2:3], v[74:75], 0, s[54:55]
	s_add_i32 s52, s76, s59
	v_lshlrev_b64 v[2:3], 6, v[2:3]
	s_add_i32 s52, s52, 3
	v_lshl_add_u64 v[2:3], v[78:79], 0, v[2:3]
	s_lshl_b64 s[54:55], s[52:53], 9
	v_lshl_add_u64 v[60:61], v[80:81], 0, s[54:55]
	global_load_dwordx2 v[118:119], v[2:3], off
	s_nop 0
	global_load_dwordx4 v[124:127], v[60:61], off
	s_branch .LBB0_643
.LBB0_642:
.LBB0_643:
	ds_read_b128 v[60:63], v103 offset:40448
	ds_read_b128 v[108:111], v104
	s_waitcnt lgkmcnt(0)
	v_mfma_f32_16x16x32_bf16 v[60:63], v[60:63], v[108:111], 0
	ds_read_b128 v[108:111], v103 offset:40512
	ds_read_b128 v[112:115], v104 offset:64
	s_waitcnt lgkmcnt(0)
	v_mfma_f32_16x16x32_bf16 v[60:63], v[108:111], v[112:115], v[60:63]
	ds_read_b128 v[108:111], v103 offset:40576
	ds_read_b128 v[112:115], v104 offset:128
	s_waitcnt lgkmcnt(0)
	v_mfma_f32_16x16x32_bf16 v[60:63], v[108:111], v[112:115], v[60:63]
	ds_read_b128 v[108:111], v103 offset:40640
	ds_read_b128 v[112:115], v104 offset:192
	s_waitcnt lgkmcnt(0)
	v_mfma_f32_16x16x32_bf16 v[60:63], v[108:111], v[112:115], v[60:63]
	s_and_saveexec_b64 s[54:55], s[10:11]
	s_cbranch_execz .LBB0_645
	v_lshlrev_b32_e32 v88, 16, v84
	v_and_b32_e32 v89, 0xffff0000, v84
	v_lshlrev_b32_e32 v84, 16, v85
	v_and_b32_e32 v85, 0xffff0000, v85
	s_add_i32 s62, s72, 64
	s_nop 0
	v_pk_add_f32 v[60:61], v[60:61], v[88:89]
	v_pk_add_f32 v[62:63], v[62:63], v[84:85]
	s_ashr_i32 s63, s62, 31
	v_cvt_pk_bf16_f32 v60, v60, v61
	v_cvt_pk_bf16_f32 v61, v62, v63
	v_lshl_add_u64 v[62:63], v[82:83], 0, s[62:63]
	v_lshlrev_b64 v[62:63], 6, v[62:63]
	v_lshl_add_u64 v[62:63], v[78:79], 0, v[62:63]
	global_store_dwordx2 v[62:63], v[60:61], off

; __device__ __forceinline__ void hg_seq(const Params& p, LAS unsigned char* lds, int task) {
;     ...
; #pragma unroll 1
;     for (int ch = 0; ch < nch; ch += 2) { body(ra, ch); if (ch + 1 < nch) body(rb, ch + 1); }
.LBB0_646:
	s_mov_b32 s59, s58
	s_branch .LBB0_605
